# LRU: one static s_setprio 1 for waves 4-7 over the chunk loop (desynchronise the two waves of a SIMD)
# baseline (speedup 1.0000x reference)
.LBB0_385:
	s_or_b64 exec, exec, s[4:5]
	s_and_b64 vcc, exec, s[6:7]
	s_barrier
	s_cbranch_vccnz .LBB0_437
	v_mbcnt_lo_u32_b32 v12, -1, 0
	v_mbcnt_hi_u32_b32 v12, -1, v12
	v_lshlrev_b32_e32 v16, 3, v188
	v_and_or_b32 v12, v12, 64, v146
	v_lshlrev_b32_e32 v139, 2, v12
	v_and_b32_e32 v12, 0x1e78, v16
	s_add_i32 s22, 0, 0x11e00
	s_add_i32 s33, 0, 0x11e80
	s_add_i32 s40, 0, 0x11f00
	s_add_i32 s41, 0, 0x11f80
	v_lshrrev_b32_e32 v116, 4, v147
	v_add_u32_e32 v143, s22, v12
	v_add_u32_e32 v147, s33, v12
	v_add_u32_e32 v149, s40, v12
	v_add_u32_e32 v150, s41, v12
	v_lshlrev_b32_e32 v12, 3, v146
	v_add_u32_e32 v159, s33, v12
	s_add_i32 s33, 0, 0x12080
	v_add_u32_e32 v160, s33, v12
	s_add_i32 s33, 0, 0x12280
	v_add_u32_e32 v161, s33, v12
	s_add_i32 s33, 0, 0x12480
	v_add_u32_e32 v162, s33, v12
	s_add_i32 s33, 0, 0x12680
	v_add_u32_e32 v163, s33, v12
	s_add_i32 s33, 0, 0x12880
	v_add_u32_e32 v164, s33, v12
	s_add_i32 s33, 0, 0x12a80
	v_add_u32_e32 v165, s33, v12
	s_add_i32 s33, 0, 0x12c80
	v_add_u32_e32 v166, s33, v12
	s_add_i32 s33, 0, 0x12100
	v_add_u32_e32 v168, s33, v12
	s_add_i32 s33, 0, 0x12300
	v_add_u32_e32 v169, s33, v12
	s_add_i32 s33, 0, 0x12500
	v_add_u32_e32 v170, s33, v12
	s_add_i32 s33, 0, 0x12700
	v_add_u32_e32 v171, s33, v12
	s_add_i32 s33, 0, 0x12900
	v_add_u32_e32 v172, s33, v12
	s_add_i32 s33, 0, 0x12b00
	v_add_u32_e32 v173, s33, v12
	s_add_i32 s33, 0, 0x12d00
	v_add_u32_e32 v175, s33, v12
	s_add_i32 s33, 0, 0x12180
	v_mul_u32_u24_e32 v1, 0x1100, v196
	s_add_i32 s14, 0, 0x13e00
	v_and_b32_e32 v4, 56, v16
	v_mul_u32_u24_e32 v11, 0x110, v146
	v_add_u32_e32 v177, s33, v12
	s_add_i32 s33, 0, 0x12380
	v_mul_u32_u24_e32 v9, 0x90, v194
	s_add_i32 s19, 0, 0x1c600
	v_lshlrev_b32_e32 v10, 1, v4
	v_add3_u32 v1, s14, v1, v11
	v_lshlrev_b32_e32 v11, 5, v181
	v_mul_u32_u24_e32 v14, 0x88, v146
	v_lshl_add_u32 v15, v181, 4, 0
	v_add_u32_e32 v178, s33, v12
	s_add_i32 s33, 0, 0x12580
	s_add_i32 s18, 0, 0x11400
	v_mov_b32_e32 v77, 0
	v_add_u32_e32 v76, -3, v193
	v_add3_u32 v123, s19, v9, v10
	v_lshl_add_u32 v13, v146, 1, s19
	s_add_i32 s19, 0, 0x11c00
	v_lshl_add_u32 v128, v14, 1, v15
	v_or_b32_e32 v14, 0x80, v11
	v_add_u32_e32 v167, s40, v12
	v_add_u32_e32 v176, s41, v12
	v_add_u32_e32 v179, s33, v12
	s_add_i32 s33, 0, 0x12780
	v_readlane_b32 s40, v254, 41
	v_lshlrev_b64 v[78:79], 11, v[76:77]
	v_add_u32_e32 v76, -3, v116
	v_lshrrev_b32_e32 v117, 4, v180
	v_lshlrev_b32_e32 v9, 4, v196
	v_add_u32_e32 v125, v1, v11
	s_movk_i32 s14, 0xfef4
	v_add_u32_e32 v126, s19, v11
	v_add_u32_e32 v127, s18, v11
	v_add_u32_e32 v130, s19, v14
	v_add_u32_e32 v131, s18, v14
	v_or_b32_e32 v14, 0x100, v11
	v_or_b32_e32 v11, 0x180, v11
	v_add_u32_e32 v180, s33, v12
	s_add_i32 s33, 0, 0x12980
	v_readlane_b32 s44, v254, 45
	v_readlane_b32 s45, v254, 46
	v_readlane_b32 s46, v254, 47
	v_readlane_b32 s47, v254, 48
	v_and_b32_e32 v0, 0x7f, v188
	s_movk_i32 s4, 0x1c00
	v_lshl_add_u32 v115, v188, 2, s18
	v_lshlrev_b64 v[80:81], 11, v[76:77]
	v_lshlrev_b32_e32 v2, 7, v190
	v_add_u32_e32 v76, -3, v117
	v_or_b32_e32 v10, v9, v146
	v_mad_i32_i24 v1, v146, s14, v1
	v_cmp_eq_u32_e64 s[14:15], 0, v181
	v_cmp_ne_u32_e64 s[16:17], 0, v181
	v_lshl_or_b32 v9, v181, 2, v9
	v_add_u32_e32 v133, s19, v14
	v_add_u32_e32 v134, s18, v14
	v_add_u32_e32 v136, s19, v11
	v_add_u32_e32 v137, s18, v11
	v_mul_u32_u24_e32 v11, 0x440, v181
	v_cmp_lt_u32_e64 s[18:19], 1, v181
	v_cmp_eq_u32_e64 s[20:21], 3, v181
	s_mov_b64 s[58:59], s[38:39]
	v_add_u32_e32 v181, s33, v12
	s_add_i32 s33, 0, 0x12b80
	v_readlane_b32 s44, v254, 2
	v_and_or_b32 v114, v16, s4, v0
	v_and_b32_e32 v0, 0x78, v16
	v_and_b32_e32 v82, 0x3f800, v2
	v_lshlrev_b64 v[84:85], 11, v[76:77]
	v_lshlrev_b32_e32 v2, 7, v195
	v_add_u32_e32 v118, 64, v194
	v_mul_u32_u24_e32 v120, 0x110, v193
	v_lshrrev_b32_e32 v121, 4, v190
	v_lshrrev_b32_e32 v122, 4, v195
	s_mov_b64 s[56:57], s[36:37]
	s_add_i32 s24, 0, 0x12000
	s_add_i32 s26, 0, 0x12200
	s_add_i32 s28, 0, 0x12400
	s_add_i32 s30, 0, 0x12600
	s_add_i32 s34, 0, 0x12800
	s_add_i32 s36, 0, 0x12a00
	s_add_i32 s38, 0, 0x12c00
	v_add_u32_e32 v182, s33, v12
	s_add_i32 s33, 0, 0x12d80
	v_lshlrev_b32_e32 v76, 4, v146
	v_readlane_b32 s54, v254, 55
	v_readlane_b32 s55, v254, 56
	v_readlane_b32 s46, v254, 4
	v_readlane_b32 s47, v254, 5
	s_movk_i32 s4, 0x80
	s_movk_i32 s8, 0x230
	v_and_b32_e32 v86, 0x41800, v2
	v_lshlrev_b32_e32 v2, 10, v194
	v_lshlrev_b32_e32 v6, 10, v118
	v_lshl_add_u32 v119, v0, 1, 0
	v_mul_u32_u24_e32 v3, 0x110, v116
	v_mul_u32_u24_e32 v5, 0x110, v121
	v_mul_u32_u24_e32 v7, 0x110, v117
	s_movk_i32 s12, 0x830
	v_mul_u32_u24_e32 v8, 0x110, v122
	v_mul_u32_u24_e32 v10, 0x110, v10
	v_add_u32_e32 v151, s22, v12
	v_add_u32_e32 v152, s24, v12
	v_add_u32_e32 v153, s26, v12
	v_add_u32_e32 v154, s28, v12
	v_add_u32_e32 v155, s30, v12
	v_add_u32_e32 v156, s34, v12
	v_add_u32_e32 v157, s36, v12
	v_add_u32_e32 v158, s38, v12
	v_mul_u32_u24_e32 v14, 0x90, v9
	v_add_u32_e32 v183, s33, v12
	v_add3_u32 v12, v120, v76, 0
	v_readlane_b32 s43, v254, 44
	v_readlane_b32 s51, v254, 52
	v_lshl_add_u64 v[88:89], s[54:55], 0, v[76:77]
	v_lshl_add_u64 v[90:91], s[56:57], 0, v[76:77]
	v_lshlrev_b32_e32 v76, 11, v9
	v_readlane_b32 s45, v254, 3
	v_readlane_b32 s46, v254, 0
	v_cmp_gt_u32_e64 s[4:5], s4, v188
	v_cmp_lt_u32_e64 s[6:7], 47, v188
	v_mov_b32_e32 v83, v77
	v_cmp_gt_u32_e64 s[8:9], s8, v188
	v_cmp_gt_u32_e64 s[10:11], 48, v188
	v_mov_b32_e32 v87, v77
	v_cmp_gt_u32_e64 s[12:13], s12, v195
	v_add_u32_e32 v124, 0x2400, v123
	v_add_u32_e32 v129, 0xd000, v128
	v_add_u32_e32 v132, 0xd040, v128
	v_add_u32_e32 v135, 0xd080, v128
	v_add_u32_e32 v138, 0xd0c0, v128
	v_or_b32_e32 v140, 64, v139
	v_or_b32_e32 v141, 0x80, v139
	v_or_b32_e32 v142, 0xc0, v139
	v_cmp_gt_u32_e64 s[22:23], 64, v188
	v_cmp_eq_u32_e64 s[24:25], 1, v196
	v_cmp_eq_u32_e64 s[26:27], 2, v196
	v_cmp_eq_u32_e64 s[28:29], 3, v196
	v_cmp_eq_u32_e64 s[30:31], 4, v196
	v_cmp_eq_u32_e64 s[34:35], 5, v196
	v_cmp_eq_u32_e64 s[36:37], 6, v196
	v_cmp_eq_u32_e64 s[38:39], 7, v196
	v_readfirstlane_b32 s88, v196
	s_nop 3
	s_cmp_ge_u32 s88, 4
	s_cbranch_scc0 .Llru_prio_done
	s_setprio 1
.Llru_prio_done:
	v_add_u32_e32 v184, 0xfffffe00, v188
	v_add_u32_e32 v185, 0x8c00, v12
	s_lshl_b32 s33, s2, 7
	s_lshl_b32 s43, s3, 7
	v_lshl_add_u64 v[92:93], s[44:45], 0, v[76:77]
	s_mov_b64 s[44:45], 0x2000
	v_lshlrev_b32_e32 v94, 1, v0
	v_lshlrev_b32_e32 v96, 1, v2
	v_lshlrev_b32_e32 v98, 1, v4
	v_lshlrev_b32_e32 v100, 1, v6
	s_mov_b32 s51, 0xbfb8aa3b
	s_mov_b32 s64, 0xb2a5705f
	s_mov_b32 s65, 0x42ce8ed0
	s_mov_b32 s66, 0xc2b17218
	s_mov_b32 s67, 0x7f800000
	s_mov_b32 s68, 0x3f2aaaab
	v_mov_b32_e32 v186, 0x3ecc95a3
	s_mov_b32 s69, 0x3f317218
	s_mov_b32 s72, 0x33800000
	v_add_u32_e32 v187, v13, v14
	s_movk_i32 s73, 0x7fff
	v_add_u32_e32 v195, v119, v3
	v_add_u32_e32 v196, v119, v5
	v_add_u32_e32 v197, v119, v7
	v_add_u32_e32 v198, v119, v8
	v_mov_b32_e32 v199, 0x7f800000
	v_add_u32_e32 v200, v15, v10
	v_add_u32_e32 v201, v1, v11
	s_mov_b32 s76, s2
	v_readlane_b32 s47, v254, 1
	v_readlane_b32 s41, v254, 42
	v_readlane_b32 s42, v254, 43
	v_readlane_b32 s48, v254, 49
	v_readlane_b32 s49, v254, 50
	v_readlane_b32 s50, v254, 51
	v_readlane_b32 s52, v254, 53
	v_readlane_b32 s53, v254, 54
	s_branch .LBB0_388

.LBB0_436:
	s_setprio 0
	v_readlane_b32 s56, v255, 12
	v_readlane_b32 s36, v254, 57
	v_readlane_b32 s70, v255, 26
	v_readlane_b32 s71, v255, 27
	v_readlane_b32 s44, v255, 1
	v_readlane_b32 s45, v255, 2
	v_readlane_b32 s57, v255, 13
	v_readlane_b32 s58, v255, 14
	v_readlane_b32 s59, v255, 15
	v_readlane_b32 s60, v255, 16
	v_readlane_b32 s61, v255, 17
	v_readlane_b32 s62, v255, 18
	v_readlane_b32 s63, v255, 19
	v_readlane_b32 s64, v255, 20
	v_readlane_b32 s65, v255, 21
	v_readlane_b32 s66, v255, 22
	v_readlane_b32 s67, v255, 23
	v_readlane_b32 s68, v255, 24
	v_readlane_b32 s69, v255, 25
	v_readlane_b32 s37, v254, 58
	v_readlane_b32 s38, v254, 59
	v_readlane_b32 s39, v254, 60
	v_readlane_b32 s40, v254, 61
	v_readlane_b32 s41, v254, 62
	v_readlane_b32 s42, v254, 63
	v_readlane_b32 s43, v255, 0
	v_readlane_b32 s46, v255, 3
	v_readlane_b32 s47, v255, 4
	v_readlane_b32 s48, v255, 5
	v_readlane_b32 s49, v255, 6
	v_readlane_b32 s50, v255, 7
	v_readlane_b32 s51, v255, 8
